# v105 + sample-item masks in LDS + coalesced kmax item loads (8 lanes per key row, DPP sum)
# speedup vs baseline: 1.0050x; 1.0021x over previous
; DI void kmax_item(const Params& p, int seq, int h, char*) {
;   const int tid = get_tid(), wid = __builtin_amdgcn_readfirstlane(tid >> 6), lane = tid & 63;
;   const bfr* kb; int S;
;   if (seq < NB_P) { kb = (const bfr*)(p.ws + W_KBP) + (long)seq * KP_PAD * 512; S = T_P; }
;   else { kb = (const bfr*)(p.ws + W_KBS) + (long)(seq - NB_P) * S_S * 512; S = S_S; }
;   float mx = 0.f;
;   for (int key = tid; key < S; key += 256) {
;     const uint4* r = (const uint4*)(kb + (long)key * 512 + h * 64);
;     float ss = 0.f;
; #pragma unroll
;     for (int i = 0; i < 8; ++i) {
;       uint4 v = r[i];
;       unsigned u[4] = {v.x, v.y, v.z, v.w};
; #pragma unroll
;       for (int j = 0; j < 4; ++j) {
;         float a = __uint_as_float(u[j] << 16), b = __uint_as_float(u[j] & 0xFFFF0000u);
;         ss += a * a + b * b;
;       }
;     }
;     mx = fmaxf(mx, ss);
;   }
; #pragma unroll
;   for (int o = 32; o >= 1; o >>= 1) mx = fmaxf(mx, __shfl_xor(mx, o));
.LBB0_4421:
	s_and_b32 s0, s2, 7
	s_lshl_b32 s0, s0, 7
	s_add_u32 s10, s6, s0
	s_addc_u32 s11, s7, 0
	v_lshrrev_b32_e32 v1, 3, v0
	v_and_b32_e32 v2, 7, v0
	v_lshlrev_b32_e32 v2, 4, v2
	v_lshl_add_u32 v2, v1, 10, v2
	v_mov_b32_e32 v8, 0
	s_mov_b32 s18, 0
.Lkm_loop:
	s_mov_b64 s[12:13], s[10:11]
	global_load_dwordx4 v[10:13], v2, s[12:13]
	s_add_u32 s12, s12, 0x8000
	s_addc_u32 s13, s13, 0
	global_load_dwordx4 v[14:17], v2, s[12:13]
	s_add_u32 s12, s12, 0x8000
	s_addc_u32 s13, s13, 0
	global_load_dwordx4 v[18:21], v2, s[12:13]
	s_add_u32 s12, s12, 0x8000
	s_addc_u32 s13, s13, 0
	global_load_dwordx4 v[22:25], v2, s[12:13]
	s_add_u32 s12, s12, 0x8000
	s_addc_u32 s13, s13, 0
	global_load_dwordx4 v[26:29], v2, s[12:13]
	s_add_u32 s12, s12, 0x8000
	s_addc_u32 s13, s13, 0
	global_load_dwordx4 v[30:33], v2, s[12:13]
	s_add_u32 s12, s12, 0x8000
	s_addc_u32 s13, s13, 0
	global_load_dwordx4 v[34:37], v2, s[12:13]
	s_add_u32 s12, s12, 0x8000
	s_addc_u32 s13, s13, 0
	global_load_dwordx4 v[38:41], v2, s[12:13]
	s_add_u32 s10, s10, 0x40000
	s_addc_u32 s11, s11, 0
	s_waitcnt vmcnt(7)
	v_lshlrev_b32_e32 v42, 16, v10
	v_and_b32_e32 v43, 0xffff0000, v10
	v_lshlrev_b32_e32 v44, 16, v11
	v_and_b32_e32 v45, 0xffff0000, v11
	v_pk_mul_f32 v[42:43], v[42:43], v[42:43]
	v_pk_fma_f32 v[42:43], v[44:45], v[44:45], v[42:43]
	v_lshlrev_b32_e32 v44, 16, v12
	v_and_b32_e32 v45, 0xffff0000, v12
	v_lshlrev_b32_e32 v46, 16, v13
	v_and_b32_e32 v47, 0xffff0000, v13
	v_pk_fma_f32 v[42:43], v[44:45], v[44:45], v[42:43]
	v_pk_fma_f32 v[42:43], v[46:47], v[46:47], v[42:43]
	s_nop 0
	v_add_f32_e32 v42, v42, v43
	s_nop 1
	v_add_f32_dpp v43, v42, v42 quad_perm:[1,0,3,2] row_mask:0xf bank_mask:0xf
	s_nop 1
	v_add_f32_dpp v42, v43, v43 quad_perm:[2,3,0,1] row_mask:0xf bank_mask:0xf
	s_nop 1
	v_add_f32_dpp v43, v42, v42 row_half_mirror row_mask:0xf bank_mask:0xf
	s_add_i32 s0, s18, 0
	v_add_u32_e32 v44, s0, v1
	v_cmp_gt_i32_e32 vcc, s16, v44
	s_nop 1
	v_cndmask_b32_e32 v43, 0, v43, vcc
	v_max_f32_e32 v8, v8, v43
	s_waitcnt vmcnt(6)
	v_lshlrev_b32_e32 v42, 16, v14
	v_and_b32_e32 v43, 0xffff0000, v14
	v_lshlrev_b32_e32 v44, 16, v15
	v_and_b32_e32 v45, 0xffff0000, v15
	v_pk_mul_f32 v[42:43], v[42:43], v[42:43]
	v_pk_fma_f32 v[42:43], v[44:45], v[44:45], v[42:43]
	v_lshlrev_b32_e32 v44, 16, v16
	v_and_b32_e32 v45, 0xffff0000, v16
	v_lshlrev_b32_e32 v46, 16, v17
	v_and_b32_e32 v47, 0xffff0000, v17
	v_pk_fma_f32 v[42:43], v[44:45], v[44:45], v[42:43]
	v_pk_fma_f32 v[42:43], v[46:47], v[46:47], v[42:43]
	s_nop 0
	v_add_f32_e32 v42, v42, v43
	s_nop 1
	v_add_f32_dpp v43, v42, v42 quad_perm:[1,0,3,2] row_mask:0xf bank_mask:0xf
	s_nop 1
	v_add_f32_dpp v42, v43, v43 quad_perm:[2,3,0,1] row_mask:0xf bank_mask:0xf
	s_nop 1
	v_add_f32_dpp v43, v42, v42 row_half_mirror row_mask:0xf bank_mask:0xf
	s_add_i32 s0, s18, 32
	v_add_u32_e32 v44, s0, v1
	v_cmp_gt_i32_e32 vcc, s16, v44
	s_nop 1
	v_cndmask_b32_e32 v43, 0, v43, vcc
	v_max_f32_e32 v8, v8, v43
	s_waitcnt vmcnt(5)
	v_lshlrev_b32_e32 v42, 16, v18
	v_and_b32_e32 v43, 0xffff0000, v18
	v_lshlrev_b32_e32 v44, 16, v19
	v_and_b32_e32 v45, 0xffff0000, v19
	v_pk_mul_f32 v[42:43], v[42:43], v[42:43]
	v_pk_fma_f32 v[42:43], v[44:45], v[44:45], v[42:43]
	v_lshlrev_b32_e32 v44, 16, v20
	v_and_b32_e32 v45, 0xffff0000, v20
	v_lshlrev_b32_e32 v46, 16, v21
	v_and_b32_e32 v47, 0xffff0000, v21
	v_pk_fma_f32 v[42:43], v[44:45], v[44:45], v[42:43]
	v_pk_fma_f32 v[42:43], v[46:47], v[46:47], v[42:43]
	s_nop 0
	v_add_f32_e32 v42, v42, v43
	s_nop 1
	v_add_f32_dpp v43, v42, v42 quad_perm:[1,0,3,2] row_mask:0xf bank_mask:0xf
	s_nop 1
	v_add_f32_dpp v42, v43, v43 quad_perm:[2,3,0,1] row_mask:0xf bank_mask:0xf
	s_nop 1
	v_add_f32_dpp v43, v42, v42 row_half_mirror row_mask:0xf bank_mask:0xf
	s_add_i32 s0, s18, 64
	v_add_u32_e32 v44, s0, v1
	v_cmp_gt_i32_e32 vcc, s16, v44
	s_nop 1
	v_cndmask_b32_e32 v43, 0, v43, vcc
	v_max_f32_e32 v8, v8, v43
	s_waitcnt vmcnt(4)
; DI void kmax_item(const Params& p, int seq, int h, char*) {
;     ...
;   for (int key = tid; key < S; key += 256) {
;     const uint4* r = (const uint4*)(kb + (long)key * 512 + h * 64);
;     float ss = 0.f;
; #pragma unroll
;     for (int i = 0; i < 8; ++i) {
;       uint4 v = r[i];
;       unsigned u[4] = {v.x, v.y, v.z, v.w};
; #pragma unroll
;       for (int j = 0; j < 4; ++j) {
;         float a = __uint_as_float(u[j] << 16), b = __uint_as_float(u[j] & 0xFFFF0000u);
;         ss += a * a + b * b;
;       }
;     }
;     mx = fmaxf(mx, ss);
;   }
	v_lshlrev_b32_e32 v42, 16, v22
	v_and_b32_e32 v43, 0xffff0000, v22
	v_lshlrev_b32_e32 v44, 16, v23
	v_and_b32_e32 v45, 0xffff0000, v23
	v_pk_mul_f32 v[42:43], v[42:43], v[42:43]
	v_pk_fma_f32 v[42:43], v[44:45], v[44:45], v[42:43]
	v_lshlrev_b32_e32 v44, 16, v24
	v_and_b32_e32 v45, 0xffff0000, v24
	v_lshlrev_b32_e32 v46, 16, v25
	v_and_b32_e32 v47, 0xffff0000, v25
	v_pk_fma_f32 v[42:43], v[44:45], v[44:45], v[42:43]
	v_pk_fma_f32 v[42:43], v[46:47], v[46:47], v[42:43]
	s_nop 0
	v_add_f32_e32 v42, v42, v43
	s_nop 1
	v_add_f32_dpp v43, v42, v42 quad_perm:[1,0,3,2] row_mask:0xf bank_mask:0xf
	s_nop 1
	v_add_f32_dpp v42, v43, v43 quad_perm:[2,3,0,1] row_mask:0xf bank_mask:0xf
	s_nop 1
	v_add_f32_dpp v43, v42, v42 row_half_mirror row_mask:0xf bank_mask:0xf
	s_add_i32 s0, s18, 96
	v_add_u32_e32 v44, s0, v1
	v_cmp_gt_i32_e32 vcc, s16, v44
	s_nop 1
	v_cndmask_b32_e32 v43, 0, v43, vcc
	v_max_f32_e32 v8, v8, v43
	s_waitcnt vmcnt(3)
	v_lshlrev_b32_e32 v42, 16, v26
	v_and_b32_e32 v43, 0xffff0000, v26
	v_lshlrev_b32_e32 v44, 16, v27
	v_and_b32_e32 v45, 0xffff0000, v27
	v_pk_mul_f32 v[42:43], v[42:43], v[42:43]
	v_pk_fma_f32 v[42:43], v[44:45], v[44:45], v[42:43]
	v_lshlrev_b32_e32 v44, 16, v28
	v_and_b32_e32 v45, 0xffff0000, v28
	v_lshlrev_b32_e32 v46, 16, v29
	v_and_b32_e32 v47, 0xffff0000, v29
	v_pk_fma_f32 v[42:43], v[44:45], v[44:45], v[42:43]
	v_pk_fma_f32 v[42:43], v[46:47], v[46:47], v[42:43]
	s_nop 0
	v_add_f32_e32 v42, v42, v43
	s_nop 1
	v_add_f32_dpp v43, v42, v42 quad_perm:[1,0,3,2] row_mask:0xf bank_mask:0xf
	s_nop 1
	v_add_f32_dpp v42, v43, v43 quad_perm:[2,3,0,1] row_mask:0xf bank_mask:0xf
	s_nop 1
	v_add_f32_dpp v43, v42, v42 row_half_mirror row_mask:0xf bank_mask:0xf
	s_add_i32 s0, s18, 128
	v_add_u32_e32 v44, s0, v1
	v_cmp_gt_i32_e32 vcc, s16, v44
	s_nop 1
	v_cndmask_b32_e32 v43, 0, v43, vcc
	v_max_f32_e32 v8, v8, v43
	s_waitcnt vmcnt(2)
	v_lshlrev_b32_e32 v42, 16, v30
	v_and_b32_e32 v43, 0xffff0000, v30
	v_lshlrev_b32_e32 v44, 16, v31
	v_and_b32_e32 v45, 0xffff0000, v31
	v_pk_mul_f32 v[42:43], v[42:43], v[42:43]
	v_pk_fma_f32 v[42:43], v[44:45], v[44:45], v[42:43]
	v_lshlrev_b32_e32 v44, 16, v32
	v_and_b32_e32 v45, 0xffff0000, v32
	v_lshlrev_b32_e32 v46, 16, v33
	v_and_b32_e32 v47, 0xffff0000, v33
	v_pk_fma_f32 v[42:43], v[44:45], v[44:45], v[42:43]
	v_pk_fma_f32 v[42:43], v[46:47], v[46:47], v[42:43]
	s_nop 0
	v_add_f32_e32 v42, v42, v43
	s_nop 1
	v_add_f32_dpp v43, v42, v42 quad_perm:[1,0,3,2] row_mask:0xf bank_mask:0xf
	s_nop 1
	v_add_f32_dpp v42, v43, v43 quad_perm:[2,3,0,1] row_mask:0xf bank_mask:0xf
	s_nop 1
	v_add_f32_dpp v43, v42, v42 row_half_mirror row_mask:0xf bank_mask:0xf
	s_add_i32 s0, s18, 160
	v_add_u32_e32 v44, s0, v1
	v_cmp_gt_i32_e32 vcc, s16, v44
	s_nop 1
	v_cndmask_b32_e32 v43, 0, v43, vcc
	v_max_f32_e32 v8, v8, v43
	s_waitcnt vmcnt(1)
	v_lshlrev_b32_e32 v42, 16, v34
	v_and_b32_e32 v43, 0xffff0000, v34
	v_lshlrev_b32_e32 v44, 16, v35
	v_and_b32_e32 v45, 0xffff0000, v35
	v_pk_mul_f32 v[42:43], v[42:43], v[42:43]
	v_pk_fma_f32 v[42:43], v[44:45], v[44:45], v[42:43]
	v_lshlrev_b32_e32 v44, 16, v36
	v_and_b32_e32 v45, 0xffff0000, v36
	v_lshlrev_b32_e32 v46, 16, v37
	v_and_b32_e32 v47, 0xffff0000, v37
	v_pk_fma_f32 v[42:43], v[44:45], v[44:45], v[42:43]
	v_pk_fma_f32 v[42:43], v[46:47], v[46:47], v[42:43]
	s_nop 0
	v_add_f32_e32 v42, v42, v43
	s_nop 1
	v_add_f32_dpp v43, v42, v42 quad_perm:[1,0,3,2] row_mask:0xf bank_mask:0xf
	s_nop 1
	v_add_f32_dpp v42, v43, v43 quad_perm:[2,3,0,1] row_mask:0xf bank_mask:0xf
	s_nop 1
	v_add_f32_dpp v43, v42, v42 row_half_mirror row_mask:0xf bank_mask:0xf
	s_add_i32 s0, s18, 192
	v_add_u32_e32 v44, s0, v1
	v_cmp_gt_i32_e32 vcc, s16, v44
	s_nop 1
	v_cndmask_b32_e32 v43, 0, v43, vcc
	v_max_f32_e32 v8, v8, v43
	s_waitcnt vmcnt(0)
	v_lshlrev_b32_e32 v42, 16, v38
	v_and_b32_e32 v43, 0xffff0000, v38
	v_lshlrev_b32_e32 v44, 16, v39
	v_and_b32_e32 v45, 0xffff0000, v39
	v_pk_mul_f32 v[42:43], v[42:43], v[42:43]
	v_pk_fma_f32 v[42:43], v[44:45], v[44:45], v[42:43]
	v_lshlrev_b32_e32 v44, 16, v40
	v_and_b32_e32 v45, 0xffff0000, v40
	v_lshlrev_b32_e32 v46, 16, v41
	v_and_b32_e32 v47, 0xffff0000, v41
	v_pk_fma_f32 v[42:43], v[44:45], v[44:45], v[42:43]
	v_pk_fma_f32 v[42:43], v[46:47], v[46:47], v[42:43]
	s_nop 0
	v_add_f32_e32 v42, v42, v43
	s_nop 1
	v_add_f32_dpp v43, v42, v42 quad_perm:[1,0,3,2] row_mask:0xf bank_mask:0xf
	s_nop 1
	v_add_f32_dpp v42, v43, v43 quad_perm:[2,3,0,1] row_mask:0xf bank_mask:0xf
	s_nop 1
	v_add_f32_dpp v43, v42, v42 row_half_mirror row_mask:0xf bank_mask:0xf
	s_add_i32 s0, s18, 224
	v_add_u32_e32 v44, s0, v1
	v_cmp_gt_i32_e32 vcc, s16, v44
	s_nop 1
	v_cndmask_b32_e32 v43, 0, v43, vcc
	v_max_f32_e32 v8, v8, v43
	s_addk_i32 s18, 0x100
	s_cmp_lt_i32 s18, s16
	s_cbranch_scc1 .Lkm_loop
